# GEMM K-loop: the redundant back-to-back s_setprio 0 / s_setprio 1 pairs inside the MFMA segments removed (loop head kept at the same byte phase)
# baseline (speedup 1.0000x reference)
; #define PG8_STAGE(bufoff, gbase, voff) do { _Pragma("unroll") for (int _i = 0; _i < 2; ++_i) \
;         __builtin_amdgcn_global_load_lds((const unsigned*)((const char*)(gbase) + (voff)[_i]), (LAS unsigned*)(lds + (bufoff) + ldsw + _i * 8192), 16, 0, 0); } while (0)
; #define PG8_LDA(dst, b, h) do { _Pragma("unroll") for (int m = 0; m < 4; ++m) _Pragma("unroll") for (int k = 0; k < 2; ++k) dst[m][k] = *(const LAS bf16x8*)(lds + PG8_SA(b, h) + aoff + m * 2048 + k * 1024); } while (0)
; #define PG8_LDB(dst, b, h) do { _Pragma("unroll") for (int n = 0; n < 2; ++n) _Pragma("unroll") for (int k = 0; k < 2; ++k) dst[n][k] = *(const LAS bf16x8*)(lds + PG8_SB(b, h) + boff + n * 2048 + k * 1024); } while (0)
; #define PG8_MMA(ai, bj, At, Bt) do { __builtin_amdgcn_s_setprio(1); _Pragma("unroll") for (int m = 0; m < 4; ++m) _Pragma("unroll") for (int n = 0; n < 2; ++n) _Pragma("unroll") for (int k = 0; k < 2; ++k) \
;         acc[ai][bj][m][n] = __builtin_amdgcn_mfma_f32_16x16x32_bf16(Bt[n][k], At[m][k], acc[ai][bj][m][n], 0, 0, 0); __builtin_amdgcn_s_setprio(0); } while (0)
; #define PG8_WAIT_V(n) asm volatile("s_waitcnt vmcnt(" #n ")" ::: "memory")
; #define PG8_WAIT_L(n) asm volatile("s_waitcnt lgkmcnt(" #n ")" ::: "memory")
; #define PG8_BAR __builtin_amdgcn_s_barrier()
; #define PG8_SCHED __builtin_amdgcn_sched_barrier(0)
; __device__ __forceinline__ void gemm_phase(LAS unsigned char* lds, const GemmP g, const EpiP e) {
;     ...
;         for (int t = 0; t < nt; t += 2) {
;             const bool last = (t == nt - 2);
;             const char* a1 = cA + (size_t)(t + 1) * kstepA;
;             const char* a2 = last ? nA : cA + (size_t)(t + 2) * kstepA; const char* b2 = last ? nB : cB + (size_t)(t + 2) * kstepB;
;             const char* a3 = a2 + kstepA; const char* b3 = b2 + kstepB;
;             PG8_LDB(B0, 0, 0); PG8_LDB(B1, 0, 1); PG8_SCHED; PG8_LDA(At, 0, 0); PG8_STAGE(PG8_SA(1, 1), a1 + hstepA, voffA);
;             PG8_WAIT_V(8); PG8_WAIT_L(0); PG8_BAR; PG8_MMA(0, 0, At, B0); PG8_MMA(0, 1, At, B1); PG8_BAR; PG8_SCHED;
;             PG8_LDA(At, 0, 1); PG8_STAGE(PG8_SB(0, 0), b2, voffB); PG8_STAGE(PG8_SB(0, 1), b2 + hstepB, voffB); PG8_STAGE(PG8_SA(0, 0), a2, voffA);
;             PG8_WAIT_V(8); PG8_WAIT_L(0); PG8_BAR; PG8_MMA(1, 0, At, B0); PG8_MMA(1, 1, At, B1); PG8_BAR; PG8_SCHED;
.LBB0_392:
	s_cmp_lt_i32 s69, 1
	s_cbranch_scc1 .LBB0_395
	s_add_u32 s24, s78, s90
	s_addc_u32 s25, s79, s7
	s_add_i32 s26, s69, -2
	s_add_u32 s27, s40, 0x100
	s_addc_u32 s28, s41, 0
	s_mov_b64 s[18:19], 0
	s_cmp_eq_u32 s99, 0
	s_cbranch_scc1 .LBB0_394
	s_mov_b32 s99, 0
	s_add_u32 s30, s18, 1
	s_addc_u32 s31, s19, 0
	s_add_u32 s16, s18, 2
	s_addc_u32 s17, s19, 0
	s_lshl_b64 s[20:21], s[16:17], s77
	s_add_u32 s19, s78, s20
	s_addc_u32 s20, s79, s21
	s_cmp_eq_u32 s26, s18
	s_cselect_b32 s21, s51, s20
	s_cselect_b32 s20, s50, s19
	s_cselect_b32 s22, s80, s27
	s_cselect_b32 s23, s81, s28
	s_add_u32 s18, s20, s38
	s_addc_u32 s19, s21, s39
	s_add_i32 s29, 0, 0x10000
	v_add_u32_e32 v96, s29, v179
	s_add_i32 s34, 0, 0x14000
	ds_read_b128 v[132:135], v96
	ds_read_b128 v[136:139], v96 offset:1024
	ds_read_b128 v[160:163], v96 offset:2048
	ds_read_b128 v[164:167], v96 offset:3072
	v_add_u32_e32 v96, s34, v179
	ds_read_b128 v[168:171], v96
	ds_read_b128 v[172:175], v96 offset:1024
	ds_read_b128 v[216:219], v96 offset:2048
	ds_read_b128 v[220:223], v96 offset:3072
	s_lshl_b64 s[30:31], s[30:31], s77
	s_add_u32 s30, s24, s30
	s_addc_u32 s31, s25, s31
	v_lshl_add_u64 v[98:99], s[30:31], 0, v[140:141]
	s_add_i32 m0, s92, 0xc000
	ds_read_b128 v[224:227], v188
	ds_read_b128 v[228:231], v188 offset:1024
	ds_read_b128 v[232:235], v188 offset:2048
	ds_read_b128 v[236:239], v188 offset:3072
	ds_read_b128 v[240:243], v188 offset:4096
	ds_read_b128 v[244:247], v188 offset:5120
	ds_read_b128 v[248:251], v188 offset:6144
	ds_read_b128 v[204:207], v188 offset:7168
	global_load_lds_dwordx4 v[98:99], off
	v_lshl_add_u64 v[98:99], s[30:31], 0, v[142:143]
	s_add_i32 m0, s92, 0xe000
	s_nop 0
	global_load_lds_dwordx4 v[98:99], off
	s_waitcnt vmcnt(24)
	s_waitcnt lgkmcnt(0)
	s_barrier
	s_setprio 1
	s_waitcnt lgkmcnt(0)
	v_mfma_f32_16x16x32_bf16 v[128:131], v[132:135], v[224:227], v[128:131]
	v_mfma_f32_16x16x32_bf16 v[124:127], v[160:163], v[224:227], v[124:127]
	v_mfma_f32_16x16x32_bf16 v[120:123], v[132:135], v[232:235], v[120:123]
	v_mfma_f32_16x16x32_bf16 v[116:119], v[160:163], v[232:235], v[116:119]
	v_mfma_f32_16x16x32_bf16 v[112:115], v[132:135], v[240:243], v[112:115]
	v_mfma_f32_16x16x32_bf16 v[108:111], v[160:163], v[240:243], v[108:111]
	v_mfma_f32_16x16x32_bf16 v[104:107], v[132:135], v[248:251], v[104:107]
	v_mfma_f32_16x16x32_bf16 v[98:101], v[160:163], v[248:251], v[100:103]
	v_mfma_f32_16x16x32_bf16 v[128:131], v[136:139], v[228:231], v[128:131]
	v_mfma_f32_16x16x32_bf16 v[124:127], v[164:167], v[228:231], v[124:127]
	v_mfma_f32_16x16x32_bf16 v[120:123], v[136:139], v[236:239], v[120:123]
	v_mfma_f32_16x16x32_bf16 v[116:119], v[164:167], v[236:239], v[116:119]
	v_mfma_f32_16x16x32_bf16 v[112:115], v[136:139], v[244:247], v[112:115]
	v_mfma_f32_16x16x32_bf16 v[108:111], v[164:167], v[244:247], v[108:111]
	v_mfma_f32_16x16x32_bf16 v[104:107], v[136:139], v[204:207], v[104:107]
	v_mfma_f32_16x16x32_bf16 v[98:101], v[164:167], v[204:207], v[98:101]
	v_mfma_f32_16x16x32_bf16 v[92:95], v[168:171], v[224:227], v[92:95]
	v_mfma_f32_16x16x32_bf16 v[88:91], v[216:219], v[224:227], v[88:91]
	v_mfma_f32_16x16x32_bf16 v[84:87], v[168:171], v[232:235], v[84:87]
	v_mfma_f32_16x16x32_bf16 v[80:83], v[216:219], v[232:235], v[80:83]
	v_mfma_f32_16x16x32_bf16 v[76:79], v[168:171], v[240:243], v[76:79]
	v_mfma_f32_16x16x32_bf16 v[72:75], v[216:219], v[240:243], v[72:75]
	v_mfma_f32_16x16x32_bf16 v[68:71], v[168:171], v[248:251], v[68:71]
	v_mfma_f32_16x16x32_bf16 v[64:67], v[216:219], v[248:251], v[64:67]
	v_mfma_f32_16x16x32_bf16 v[92:95], v[172:175], v[228:231], v[92:95]
	v_mfma_f32_16x16x32_bf16 v[88:91], v[220:223], v[228:231], v[88:91]
	v_mfma_f32_16x16x32_bf16 v[84:87], v[172:175], v[236:239], v[84:87]
	v_mfma_f32_16x16x32_bf16 v[80:83], v[220:223], v[236:239], v[80:83]
	v_mfma_f32_16x16x32_bf16 v[76:79], v[172:175], v[244:247], v[76:79]
	v_mfma_f32_16x16x32_bf16 v[72:75], v[220:223], v[244:247], v[72:75]
	v_mfma_f32_16x16x32_bf16 v[68:71], v[172:175], v[204:207], v[68:71]
	v_mfma_f32_16x16x32_bf16 v[64:67], v[220:223], v[204:207], v[64:67]
	s_setprio 0
	s_barrier
	s_add_i32 s29, s29, s91
	v_lshl_add_u64 v[176:177], s[22:23], 0, v[146:147]
	s_mov_b32 m0, s29
	ds_read_b128 v[204:207], v188 offset:16384
	ds_read_b128 v[224:227], v188 offset:17408
	ds_read_b128 v[228:231], v188 offset:18432
	ds_read_b128 v[232:235], v188 offset:19456
	ds_read_b128 v[236:239], v188 offset:20480
	ds_read_b128 v[240:243], v188 offset:21504
	ds_read_b128 v[244:247], v188 offset:22528
	ds_read_b128 v[248:251], v188 offset:23552
	global_load_lds_dwordx4 v[176:177], off
	s_add_i32 m0, s29, 0x2000
	v_lshl_add_u64 v[210:211], s[22:23], 0, v[144:145]
	s_add_u32 s22, s22, s48
	s_addc_u32 s23, s23, s49
	s_add_i32 s29, s34, s91
	global_load_lds_dwordx4 v[210:211], off
	v_lshl_add_u64 v[212:213], s[22:23], 0, v[146:147]
	s_mov_b32 m0, s29
	v_lshl_add_u64 v[190:191], s[22:23], 0, v[144:145]
	global_load_lds_dwordx4 v[212:213], off
	s_add_i32 m0, s29, 0x2000
	v_lshl_add_u64 v[102:103], s[20:21], 0, v[140:141]
	global_load_lds_dwordx4 v[190:191], off
	s_mov_b32 m0, s92
	s_nop 0
	global_load_lds_dwordx4 v[102:103], off
	v_lshl_add_u64 v[102:103], s[20:21], 0, v[142:143]
	s_mov_b32 m0, s93
	s_nop 0
	global_load_lds_dwordx4 v[102:103], off
	s_waitcnt vmcnt(24)
	s_waitcnt lgkmcnt(0)
	s_barrier
; #define PG8_STAGE(bufoff, gbase, voff) do { _Pragma("unroll") for (int _i = 0; _i < 2; ++_i) \
;         __builtin_amdgcn_global_load_lds((const unsigned*)((const char*)(gbase) + (voff)[_i]), (LAS unsigned*)(lds + (bufoff) + ldsw + _i * 8192), 16, 0, 0); } while (0)
; #define PG8_LDA(dst, b, h) do { _Pragma("unroll") for (int m = 0; m < 4; ++m) _Pragma("unroll") for (int k = 0; k < 2; ++k) dst[m][k] = *(const LAS bf16x8*)(lds + PG8_SA(b, h) + aoff + m * 2048 + k * 1024); } while (0)
; #define PG8_LDB(dst, b, h) do { _Pragma("unroll") for (int n = 0; n < 2; ++n) _Pragma("unroll") for (int k = 0; k < 2; ++k) dst[n][k] = *(const LAS bf16x8*)(lds + PG8_SB(b, h) + boff + n * 2048 + k * 1024); } while (0)
; #define PG8_MMA(ai, bj, At, Bt) do { __builtin_amdgcn_s_setprio(1); _Pragma("unroll") for (int m = 0; m < 4; ++m) _Pragma("unroll") for (int n = 0; n < 2; ++n) _Pragma("unroll") for (int k = 0; k < 2; ++k) \
;         acc[ai][bj][m][n] = __builtin_amdgcn_mfma_f32_16x16x32_bf16(Bt[n][k], At[m][k], acc[ai][bj][m][n], 0, 0, 0); __builtin_amdgcn_s_setprio(0); } while (0)
; #define PG8_WAIT_V(n) asm volatile("s_waitcnt vmcnt(" #n ")" ::: "memory")
; #define PG8_WAIT_L(n) asm volatile("s_waitcnt lgkmcnt(" #n ")" ::: "memory")
; #define PG8_BAR __builtin_amdgcn_s_barrier()
; #define PG8_SCHED __builtin_amdgcn_sched_barrier(0)
; __device__ __forceinline__ void gemm_phase(LAS unsigned char* lds, const GemmP g, const EpiP e) {
;     ...
;             PG8_WAIT_V(8); PG8_WAIT_L(0); PG8_BAR; PG8_MMA(1, 0, At, B0); PG8_MMA(1, 1, At, B1); PG8_BAR; PG8_SCHED;
;             PG8_LDB(B0, 1, 0); PG8_LDB(B1, 1, 1); PG8_SCHED; PG8_LDA(At, 1, 0); PG8_STAGE(PG8_SA(0, 1), a2 + hstepA, voffA);
;             PG8_WAIT_V(8); PG8_WAIT_L(0); PG8_BAR; PG8_MMA(0, 0, At, B0); PG8_MMA(0, 1, At, B1); PG8_BAR; PG8_SCHED;
;             PG8_LDA(At, 1, 1); PG8_STAGE(PG8_SB(1, 0), b3, voffB); PG8_STAGE(PG8_SB(1, 1), b3 + hstepB, voffB); PG8_STAGE(PG8_SA(1, 0), a3, voffA);
	s_setprio 1
	s_waitcnt lgkmcnt(0)
	v_mfma_f32_16x16x32_bf16 v[60:63], v[132:135], v[204:207], v[60:63]
	v_mfma_f32_16x16x32_bf16 v[56:59], v[160:163], v[204:207], v[56:59]
	v_mfma_f32_16x16x32_bf16 v[52:55], v[132:135], v[228:231], v[52:55]
	v_mfma_f32_16x16x32_bf16 v[48:51], v[160:163], v[228:231], v[48:51]
	v_mfma_f32_16x16x32_bf16 v[44:47], v[132:135], v[236:239], v[44:47]
	v_mfma_f32_16x16x32_bf16 v[40:43], v[160:163], v[236:239], v[40:43]
	v_mfma_f32_16x16x32_bf16 v[36:39], v[132:135], v[244:247], v[36:39]
	v_mfma_f32_16x16x32_bf16 v[32:35], v[160:163], v[244:247], v[32:35]
	v_mfma_f32_16x16x32_bf16 v[60:63], v[136:139], v[224:227], v[60:63]
	v_mfma_f32_16x16x32_bf16 v[56:59], v[164:167], v[224:227], v[56:59]
	v_mfma_f32_16x16x32_bf16 v[52:55], v[136:139], v[232:235], v[52:55]
	v_mfma_f32_16x16x32_bf16 v[48:51], v[164:167], v[232:235], v[48:51]
	v_mfma_f32_16x16x32_bf16 v[44:47], v[136:139], v[240:243], v[44:47]
	v_mfma_f32_16x16x32_bf16 v[40:43], v[164:167], v[240:243], v[40:43]
	v_mfma_f32_16x16x32_bf16 v[36:39], v[136:139], v[248:251], v[36:39]
	v_mfma_f32_16x16x32_bf16 v[32:35], v[164:167], v[248:251], v[32:35]
	v_mfma_f32_16x16x32_bf16 v[28:31], v[168:171], v[204:207], v[28:31]
	v_mfma_f32_16x16x32_bf16 v[24:27], v[216:219], v[204:207], v[24:27]
	v_mfma_f32_16x16x32_bf16 v[20:23], v[168:171], v[228:231], v[20:23]
	v_mfma_f32_16x16x32_bf16 v[16:19], v[216:219], v[228:231], v[16:19]
	v_mfma_f32_16x16x32_bf16 v[12:15], v[168:171], v[236:239], v[12:15]
	v_mfma_f32_16x16x32_bf16 v[8:11], v[216:219], v[236:239], v[8:11]
	v_mfma_f32_16x16x32_bf16 v[4:7], v[168:171], v[244:247], v[4:7]
	v_mfma_f32_16x16x32_bf16 v[0:3], v[216:219], v[244:247], v[0:3]
	v_mfma_f32_16x16x32_bf16 v[28:31], v[172:175], v[224:227], v[28:31]
	v_mfma_f32_16x16x32_bf16 v[24:27], v[220:223], v[224:227], v[24:27]
	v_mfma_f32_16x16x32_bf16 v[20:23], v[172:175], v[232:235], v[20:23]
	v_mfma_f32_16x16x32_bf16 v[16:19], v[220:223], v[232:235], v[16:19]
	v_mfma_f32_16x16x32_bf16 v[12:15], v[172:175], v[240:243], v[12:15]
	v_mfma_f32_16x16x32_bf16 v[8:11], v[220:223], v[240:243], v[8:11]
	v_mfma_f32_16x16x32_bf16 v[4:7], v[172:175], v[248:251], v[4:7]
	v_mfma_f32_16x16x32_bf16 v[0:3], v[220:223], v[248:251], v[0:3]
	s_setprio 0
	s_barrier
	s_add_i32 s22, 0, 0x18000
	v_add_u32_e32 v96, s22, v179
	s_add_i32 s23, 0, 0x1c000
	ds_read_b128 v[132:135], v96
	ds_read_b128 v[136:139], v96 offset:1024
	ds_read_b128 v[160:163], v96 offset:2048
	ds_read_b128 v[164:167], v96 offset:3072
	v_add_u32_e32 v96, s23, v179
	ds_read_b128 v[168:171], v96
	ds_read_b128 v[172:175], v96 offset:1024
	ds_read_b128 v[204:207], v96 offset:2048
	ds_read_b128 v[216:219], v96 offset:3072
	s_add_u32 s20, s20, s90
	s_addc_u32 s21, s21, s7
	s_mov_b32 m0, s73
	v_lshl_add_u64 v[102:103], s[20:21], 0, v[140:141]
	ds_read_b128 v[220:223], v188 offset:32768
	ds_read_b128 v[224:227], v188 offset:33792
	ds_read_b128 v[228:231], v188 offset:34816
	ds_read_b128 v[232:235], v188 offset:35840
	ds_read_b128 v[236:239], v188 offset:36864
	ds_read_b128 v[240:243], v188 offset:37888
	ds_read_b128 v[244:247], v188 offset:38912
	ds_read_b128 v[248:251], v188 offset:39936
	global_load_lds_dwordx4 v[102:103], off
	v_lshl_add_u64 v[102:103], s[20:21], 0, v[142:143]
	s_mov_b32 m0, s4
	s_nop 0
	global_load_lds_dwordx4 v[102:103], off
	s_waitcnt vmcnt(8)
	s_waitcnt lgkmcnt(0)
	s_barrier
	s_setprio 1
	s_waitcnt lgkmcnt(0)
	v_mfma_f32_16x16x32_bf16 v[128:131], v[132:135], v[220:223], v[128:131]
	v_mfma_f32_16x16x32_bf16 v[124:127], v[160:163], v[220:223], v[124:127]
	v_mfma_f32_16x16x32_bf16 v[120:123], v[132:135], v[228:231], v[120:123]
	v_mfma_f32_16x16x32_bf16 v[116:119], v[160:163], v[228:231], v[116:119]
	v_mfma_f32_16x16x32_bf16 v[112:115], v[132:135], v[236:239], v[112:115]
	v_mfma_f32_16x16x32_bf16 v[108:111], v[160:163], v[236:239], v[108:111]
	v_mfma_f32_16x16x32_bf16 v[102:105], v[132:135], v[244:247], v[104:107]
	v_mfma_f32_16x16x32_bf16 v[98:101], v[160:163], v[244:247], v[98:101]
	v_mfma_f32_16x16x32_bf16 v[128:131], v[136:139], v[224:227], v[128:131]
	v_mfma_f32_16x16x32_bf16 v[124:127], v[164:167], v[224:227], v[124:127]
	v_mfma_f32_16x16x32_bf16 v[120:123], v[136:139], v[232:235], v[120:123]
	v_mfma_f32_16x16x32_bf16 v[116:119], v[164:167], v[232:235], v[116:119]
	v_mfma_f32_16x16x32_bf16 v[112:115], v[136:139], v[240:243], v[112:115]
	v_mfma_f32_16x16x32_bf16 v[108:111], v[164:167], v[240:243], v[108:111]
	v_mfma_f32_16x16x32_bf16 v[104:107], v[136:139], v[248:251], v[102:105]
	v_mfma_f32_16x16x32_bf16 v[100:103], v[164:167], v[248:251], v[98:101]
	v_mfma_f32_16x16x32_bf16 v[92:95], v[168:171], v[220:223], v[92:95]
	v_mfma_f32_16x16x32_bf16 v[88:91], v[204:207], v[220:223], v[88:91]
	v_mfma_f32_16x16x32_bf16 v[84:87], v[168:171], v[228:231], v[84:87]
	v_mfma_f32_16x16x32_bf16 v[80:83], v[204:207], v[228:231], v[80:83]
	v_mfma_f32_16x16x32_bf16 v[76:79], v[168:171], v[236:239], v[76:79]
	v_mfma_f32_16x16x32_bf16 v[72:75], v[204:207], v[236:239], v[72:75]
	v_mfma_f32_16x16x32_bf16 v[68:71], v[168:171], v[244:247], v[68:71]
	v_mfma_f32_16x16x32_bf16 v[64:67], v[204:207], v[244:247], v[64:67]
	v_mfma_f32_16x16x32_bf16 v[92:95], v[172:175], v[224:227], v[92:95]
	v_mfma_f32_16x16x32_bf16 v[88:91], v[216:219], v[224:227], v[88:91]
	v_mfma_f32_16x16x32_bf16 v[84:87], v[172:175], v[232:235], v[84:87]
	v_mfma_f32_16x16x32_bf16 v[80:83], v[216:219], v[232:235], v[80:83]
	v_mfma_f32_16x16x32_bf16 v[76:79], v[172:175], v[240:243], v[76:79]
	v_mfma_f32_16x16x32_bf16 v[72:75], v[216:219], v[240:243], v[72:75]
	v_mfma_f32_16x16x32_bf16 v[68:71], v[172:175], v[248:251], v[68:71]
	v_mfma_f32_16x16x32_bf16 v[64:67], v[216:219], v[248:251], v[64:67]
	s_setprio 0
	s_barrier
; #define PG8_STAGE(bufoff, gbase, voff) do { _Pragma("unroll") for (int _i = 0; _i < 2; ++_i) \
;         __builtin_amdgcn_global_load_lds((const unsigned*)((const char*)(gbase) + (voff)[_i]), (LAS unsigned*)(lds + (bufoff) + ldsw + _i * 8192), 16, 0, 0); } while (0)
; #define PG8_LDA(dst, b, h) do { _Pragma("unroll") for (int m = 0; m < 4; ++m) _Pragma("unroll") for (int k = 0; k < 2; ++k) dst[m][k] = *(const LAS bf16x8*)(lds + PG8_SA(b, h) + aoff + m * 2048 + k * 1024); } while (0)
; #define PG8_LDB(dst, b, h) do { _Pragma("unroll") for (int n = 0; n < 2; ++n) _Pragma("unroll") for (int k = 0; k < 2; ++k) dst[n][k] = *(const LAS bf16x8*)(lds + PG8_SB(b, h) + boff + n * 2048 + k * 1024); } while (0)
; #define PG8_MMA(ai, bj, At, Bt) do { __builtin_amdgcn_s_setprio(1); _Pragma("unroll") for (int m = 0; m < 4; ++m) _Pragma("unroll") for (int n = 0; n < 2; ++n) _Pragma("unroll") for (int k = 0; k < 2; ++k) \
;         acc[ai][bj][m][n] = __builtin_amdgcn_mfma_f32_16x16x32_bf16(Bt[n][k], At[m][k], acc[ai][bj][m][n], 0, 0, 0); __builtin_amdgcn_s_setprio(0); } while (0)
; #define PG8_WAIT_V(n) asm volatile("s_waitcnt vmcnt(" #n ")" ::: "memory")
; #define PG8_WAIT_L(n) asm volatile("s_waitcnt lgkmcnt(" #n ")" ::: "memory")
; #define PG8_BAR __builtin_amdgcn_s_barrier()
; #define PG8_SCHED __builtin_amdgcn_sched_barrier(0)
; __device__ __forceinline__ void gemm_phase(LAS unsigned char* lds, const GemmP g, const EpiP e) {
;     ...
;         for (int t = 0; t < nt; t += 2) {
;             const bool last = (t == nt - 2);
;             const char* a1 = cA + (size_t)(t + 1) * kstepA;
;             const char* a2 = last ? nA : cA + (size_t)(t + 2) * kstepA; const char* b2 = last ? nB : cB + (size_t)(t + 2) * kstepB;
;             const char* a3 = a2 + kstepA; const char* b3 = b2 + kstepB;
;             PG8_LDB(B0, 0, 0); PG8_LDB(B1, 0, 1); PG8_SCHED; PG8_LDA(At, 0, 0); PG8_STAGE(PG8_SA(1, 1), a1 + hstepA, voffA);
;     ...
;             PG8_LDA(At, 1, 1); PG8_STAGE(PG8_SB(1, 0), b3, voffB); PG8_STAGE(PG8_SB(1, 1), b3 + hstepB, voffB); PG8_STAGE(PG8_SA(1, 0), a3, voffA);
;             PG8_WAIT_V(8); PG8_WAIT_L(0); PG8_BAR; PG8_MMA(1, 0, At, B0); PG8_MMA(1, 1, At, B1); PG8_BAR; PG8_SCHED;
;         }
	s_add_i32 s20, s22, s91
	v_lshl_add_u64 v[98:99], v[176:177], 0, s[96:97]
	s_mov_b32 m0, s20
	ds_read_b128 v[220:223], v188 offset:49152
	ds_read_b128 v[224:227], v188 offset:50176
	ds_read_b128 v[228:231], v188 offset:51200
	ds_read_b128 v[232:235], v188 offset:52224
	ds_read_b128 v[236:239], v188 offset:53248
	ds_read_b128 v[240:243], v188 offset:54272
	ds_read_b128 v[244:247], v188 offset:55296
	ds_read_b128 v[248:251], v188 offset:56320
	global_load_lds_dwordx4 v[98:99], off
	v_lshl_add_u64 v[98:99], v[210:211], 0, s[96:97]
	s_add_i32 m0, s20, 0x2000
	s_add_i32 s20, s23, s91
	global_load_lds_dwordx4 v[98:99], off
	v_lshl_add_u64 v[98:99], v[212:213], 0, s[96:97]
	s_mov_b32 m0, s20
	s_nop 0
	global_load_lds_dwordx4 v[98:99], off
	v_lshl_add_u64 v[98:99], v[190:191], 0, s[96:97]
	s_add_i32 m0, s20, 0x2000
	s_nop 0
	global_load_lds_dwordx4 v[98:99], off
	v_lshl_add_u64 v[98:99], s[18:19], 0, v[140:141]
	s_mov_b32 m0, s5
	s_nop 0
	global_load_lds_dwordx4 v[98:99], off
	v_lshl_add_u64 v[98:99], s[18:19], 0, v[142:143]
	s_mov_b32 m0, s44
	s_nop 0
	global_load_lds_dwordx4 v[98:99], off
	s_waitcnt vmcnt(8)
	s_waitcnt lgkmcnt(0)
	s_barrier
	s_setprio 1
	s_waitcnt lgkmcnt(0)
	v_mfma_f32_16x16x32_bf16 v[60:63], v[132:135], v[220:223], v[60:63]
	v_mfma_f32_16x16x32_bf16 v[56:59], v[160:163], v[220:223], v[56:59]
	v_mfma_f32_16x16x32_bf16 v[52:55], v[132:135], v[228:231], v[52:55]
	v_mfma_f32_16x16x32_bf16 v[48:51], v[160:163], v[228:231], v[48:51]
	v_mfma_f32_16x16x32_bf16 v[44:47], v[132:135], v[236:239], v[44:47]
	v_mfma_f32_16x16x32_bf16 v[40:43], v[160:163], v[236:239], v[40:43]
	v_mfma_f32_16x16x32_bf16 v[36:39], v[132:135], v[244:247], v[36:39]
	v_mfma_f32_16x16x32_bf16 v[32:35], v[160:163], v[244:247], v[32:35]
	v_mfma_f32_16x16x32_bf16 v[60:63], v[136:139], v[224:227], v[60:63]
	v_mfma_f32_16x16x32_bf16 v[56:59], v[164:167], v[224:227], v[56:59]
	v_mfma_f32_16x16x32_bf16 v[52:55], v[136:139], v[232:235], v[52:55]
	v_mfma_f32_16x16x32_bf16 v[48:51], v[164:167], v[232:235], v[48:51]
	v_mfma_f32_16x16x32_bf16 v[44:47], v[136:139], v[240:243], v[44:47]
	v_mfma_f32_16x16x32_bf16 v[40:43], v[164:167], v[240:243], v[40:43]
	v_mfma_f32_16x16x32_bf16 v[36:39], v[136:139], v[248:251], v[36:39]
	v_mfma_f32_16x16x32_bf16 v[32:35], v[164:167], v[248:251], v[32:35]
	v_mfma_f32_16x16x32_bf16 v[28:31], v[168:171], v[220:223], v[28:31]
	v_mfma_f32_16x16x32_bf16 v[24:27], v[204:207], v[220:223], v[24:27]
	v_mfma_f32_16x16x32_bf16 v[20:23], v[168:171], v[228:231], v[20:23]
	v_mfma_f32_16x16x32_bf16 v[16:19], v[204:207], v[228:231], v[16:19]
	v_mfma_f32_16x16x32_bf16 v[12:15], v[168:171], v[236:239], v[12:15]
	v_mfma_f32_16x16x32_bf16 v[8:11], v[204:207], v[236:239], v[8:11]
	v_mfma_f32_16x16x32_bf16 v[4:7], v[168:171], v[244:247], v[4:7]
	v_mfma_f32_16x16x32_bf16 v[0:3], v[204:207], v[244:247], v[0:3]
	v_mfma_f32_16x16x32_bf16 v[28:31], v[172:175], v[224:227], v[28:31]
	v_mfma_f32_16x16x32_bf16 v[24:27], v[216:219], v[224:227], v[24:27]
	v_mfma_f32_16x16x32_bf16 v[20:23], v[172:175], v[232:235], v[20:23]
	v_mfma_f32_16x16x32_bf16 v[16:19], v[216:219], v[232:235], v[16:19]
	v_mfma_f32_16x16x32_bf16 v[12:15], v[172:175], v[240:243], v[12:15]
	v_mfma_f32_16x16x32_bf16 v[8:11], v[216:219], v[240:243], v[8:11]
	v_mfma_f32_16x16x32_bf16 v[4:7], v[172:175], v[248:251], v[4:7]
	v_mfma_f32_16x16x32_bf16 v[0:3], v[216:219], v[248:251], v[0:3]
	s_setprio 0
	s_barrier
	s_add_u32 s27, s27, 0x100
	s_addc_u32 s28, s28, 0
	s_cmp_ge_i32 s16, s69
	s_mov_b64 s[18:19], s[16:17]
	s_cbranch_scc0 .LBB0_394
	s_branch .LBB0_395
	.p2align 6
	s_nop 0
	s_nop 0
	s_nop 0
	s_nop 0
	s_nop 0
	s_nop 0
	s_nop 0
	s_nop 0
.LBB0_394:
	s_add_u32 s30, s18, 1
	s_addc_u32 s31, s19, 0
	s_add_u32 s16, s18, 2
	s_addc_u32 s17, s19, 0
	s_lshl_b64 s[20:21], s[16:17], s77
	s_add_u32 s19, s78, s20
	s_addc_u32 s20, s79, s21
	s_cmp_eq_u32 s26, s18
	s_cselect_b32 s21, s51, s20
	s_cselect_b32 s20, s50, s19
	s_cselect_b32 s22, s80, s27
	s_cselect_b32 s23, s81, s28
	s_add_u32 s18, s20, s38
	s_addc_u32 s19, s21, s39
	s_add_i32 s29, 0, 0x10000
	v_add_u32_e32 v96, s29, v179
	s_add_i32 s34, 0, 0x14000
	ds_read_b128 v[132:135], v96
	ds_read_b128 v[136:139], v96 offset:1024
	ds_read_b128 v[160:163], v96 offset:2048
	ds_read_b128 v[164:167], v96 offset:3072
	v_add_u32_e32 v96, s34, v179
	ds_read_b128 v[168:171], v96
	ds_read_b128 v[172:175], v96 offset:1024
	ds_read_b128 v[216:219], v96 offset:2048
	ds_read_b128 v[220:223], v96 offset:3072
	s_lshl_b64 s[30:31], s[30:31], s77
	s_add_u32 s30, s24, s30
	s_addc_u32 s31, s25, s31
	v_lshl_add_u64 v[98:99], s[30:31], 0, v[140:141]
	s_add_i32 m0, s92, 0xc000
	ds_read_b128 v[224:227], v188
	ds_read_b128 v[228:231], v188 offset:1024
	ds_read_b128 v[232:235], v188 offset:2048
	ds_read_b128 v[236:239], v188 offset:3072
	ds_read_b128 v[240:243], v188 offset:4096
	ds_read_b128 v[244:247], v188 offset:5120
	ds_read_b128 v[248:251], v188 offset:6144
	ds_read_b128 v[204:207], v188 offset:7168
	global_load_lds_dwordx4 v[98:99], off
	v_lshl_add_u64 v[98:99], s[30:31], 0, v[142:143]
	s_add_i32 m0, s92, 0xe000
	s_nop 0
	global_load_lds_dwordx4 v[98:99], off
	s_waitcnt vmcnt(8)
	s_waitcnt lgkmcnt(0)
	s_barrier
; #define PG8_STAGE(bufoff, gbase, voff) do { _Pragma("unroll") for (int _i = 0; _i < 2; ++_i) \
;         __builtin_amdgcn_global_load_lds((const unsigned*)((const char*)(gbase) + (voff)[_i]), (LAS unsigned*)(lds + (bufoff) + ldsw + _i * 8192), 16, 0, 0); } while (0)
; #define PG8_LDA(dst, b, h) do { _Pragma("unroll") for (int m = 0; m < 4; ++m) _Pragma("unroll") for (int k = 0; k < 2; ++k) dst[m][k] = *(const LAS bf16x8*)(lds + PG8_SA(b, h) + aoff + m * 2048 + k * 1024); } while (0)
; #define PG8_LDB(dst, b, h) do { _Pragma("unroll") for (int n = 0; n < 2; ++n) _Pragma("unroll") for (int k = 0; k < 2; ++k) dst[n][k] = *(const LAS bf16x8*)(lds + PG8_SB(b, h) + boff + n * 2048 + k * 1024); } while (0)
; #define PG8_MMA(ai, bj, At, Bt) do { __builtin_amdgcn_s_setprio(1); _Pragma("unroll") for (int m = 0; m < 4; ++m) _Pragma("unroll") for (int n = 0; n < 2; ++n) _Pragma("unroll") for (int k = 0; k < 2; ++k) \
;         acc[ai][bj][m][n] = __builtin_amdgcn_mfma_f32_16x16x32_bf16(Bt[n][k], At[m][k], acc[ai][bj][m][n], 0, 0, 0); __builtin_amdgcn_s_setprio(0); } while (0)
; #define PG8_WAIT_V(n) asm volatile("s_waitcnt vmcnt(" #n ")" ::: "memory")
; #define PG8_WAIT_L(n) asm volatile("s_waitcnt lgkmcnt(" #n ")" ::: "memory")
; #define PG8_BAR __builtin_amdgcn_s_barrier()
; #define PG8_SCHED __builtin_amdgcn_sched_barrier(0)
; __device__ __forceinline__ void gemm_phase(LAS unsigned char* lds, const GemmP g, const EpiP e) {
;     ...
;             PG8_LDB(B0, 0, 0); PG8_LDB(B1, 0, 1); PG8_SCHED; PG8_LDA(At, 0, 0); PG8_STAGE(PG8_SA(1, 1), a1 + hstepA, voffA);
;             PG8_WAIT_V(8); PG8_WAIT_L(0); PG8_BAR; PG8_MMA(0, 0, At, B0); PG8_MMA(0, 1, At, B1); PG8_BAR; PG8_SCHED;
;             PG8_LDA(At, 0, 1); PG8_STAGE(PG8_SB(0, 0), b2, voffB); PG8_STAGE(PG8_SB(0, 1), b2 + hstepB, voffB); PG8_STAGE(PG8_SA(0, 0), a2, voffA);
;             PG8_WAIT_V(8); PG8_WAIT_L(0); PG8_BAR; PG8_MMA(1, 0, At, B0); PG8_MMA(1, 1, At, B1); PG8_BAR; PG8_SCHED;
	s_setprio 1
	s_waitcnt lgkmcnt(0)
	v_mfma_f32_16x16x32_bf16 v[128:131], v[132:135], v[224:227], v[128:131]
	v_mfma_f32_16x16x32_bf16 v[124:127], v[160:163], v[224:227], v[124:127]
	v_mfma_f32_16x16x32_bf16 v[120:123], v[132:135], v[232:235], v[120:123]
	v_mfma_f32_16x16x32_bf16 v[116:119], v[160:163], v[232:235], v[116:119]
	v_mfma_f32_16x16x32_bf16 v[112:115], v[132:135], v[240:243], v[112:115]
	v_mfma_f32_16x16x32_bf16 v[108:111], v[160:163], v[240:243], v[108:111]
	v_mfma_f32_16x16x32_bf16 v[104:107], v[132:135], v[248:251], v[104:107]
	v_mfma_f32_16x16x32_bf16 v[98:101], v[160:163], v[248:251], v[100:103]
	v_mfma_f32_16x16x32_bf16 v[128:131], v[136:139], v[228:231], v[128:131]
	v_mfma_f32_16x16x32_bf16 v[124:127], v[164:167], v[228:231], v[124:127]
	v_mfma_f32_16x16x32_bf16 v[120:123], v[136:139], v[236:239], v[120:123]
	v_mfma_f32_16x16x32_bf16 v[116:119], v[164:167], v[236:239], v[116:119]
	v_mfma_f32_16x16x32_bf16 v[112:115], v[136:139], v[244:247], v[112:115]
	v_mfma_f32_16x16x32_bf16 v[108:111], v[164:167], v[244:247], v[108:111]
	v_mfma_f32_16x16x32_bf16 v[104:107], v[136:139], v[204:207], v[104:107]
	v_mfma_f32_16x16x32_bf16 v[98:101], v[164:167], v[204:207], v[98:101]
	v_mfma_f32_16x16x32_bf16 v[92:95], v[168:171], v[224:227], v[92:95]
	v_mfma_f32_16x16x32_bf16 v[88:91], v[216:219], v[224:227], v[88:91]
	v_mfma_f32_16x16x32_bf16 v[84:87], v[168:171], v[232:235], v[84:87]
	v_mfma_f32_16x16x32_bf16 v[80:83], v[216:219], v[232:235], v[80:83]
	v_mfma_f32_16x16x32_bf16 v[76:79], v[168:171], v[240:243], v[76:79]
	v_mfma_f32_16x16x32_bf16 v[72:75], v[216:219], v[240:243], v[72:75]
	v_mfma_f32_16x16x32_bf16 v[68:71], v[168:171], v[248:251], v[68:71]
	v_mfma_f32_16x16x32_bf16 v[64:67], v[216:219], v[248:251], v[64:67]
	v_mfma_f32_16x16x32_bf16 v[92:95], v[172:175], v[228:231], v[92:95]
	v_mfma_f32_16x16x32_bf16 v[88:91], v[220:223], v[228:231], v[88:91]
	v_mfma_f32_16x16x32_bf16 v[84:87], v[172:175], v[236:239], v[84:87]
	v_mfma_f32_16x16x32_bf16 v[80:83], v[220:223], v[236:239], v[80:83]
	v_mfma_f32_16x16x32_bf16 v[76:79], v[172:175], v[244:247], v[76:79]
	v_mfma_f32_16x16x32_bf16 v[72:75], v[220:223], v[244:247], v[72:75]
	v_mfma_f32_16x16x32_bf16 v[68:71], v[172:175], v[204:207], v[68:71]
	v_mfma_f32_16x16x32_bf16 v[64:67], v[220:223], v[204:207], v[64:67]
	s_setprio 0
	s_barrier
	s_add_i32 s29, s29, s91
	v_lshl_add_u64 v[176:177], s[22:23], 0, v[146:147]
	s_mov_b32 m0, s29
	ds_read_b128 v[204:207], v188 offset:16384
	ds_read_b128 v[224:227], v188 offset:17408
	ds_read_b128 v[228:231], v188 offset:18432
	ds_read_b128 v[232:235], v188 offset:19456
	ds_read_b128 v[236:239], v188 offset:20480
	ds_read_b128 v[240:243], v188 offset:21504
	ds_read_b128 v[244:247], v188 offset:22528
	ds_read_b128 v[248:251], v188 offset:23552
	global_load_lds_dwordx4 v[176:177], off
	s_add_i32 m0, s29, 0x2000
	v_lshl_add_u64 v[210:211], s[22:23], 0, v[144:145]
	s_add_u32 s22, s22, s48
	s_addc_u32 s23, s23, s49
	s_add_i32 s29, s34, s91
	global_load_lds_dwordx4 v[210:211], off
	v_lshl_add_u64 v[212:213], s[22:23], 0, v[146:147]
	s_mov_b32 m0, s29
	v_lshl_add_u64 v[190:191], s[22:23], 0, v[144:145]
	global_load_lds_dwordx4 v[212:213], off
	s_add_i32 m0, s29, 0x2000
	v_lshl_add_u64 v[102:103], s[20:21], 0, v[140:141]
	global_load_lds_dwordx4 v[190:191], off
	s_mov_b32 m0, s92
	s_nop 0
	global_load_lds_dwordx4 v[102:103], off
	v_lshl_add_u64 v[102:103], s[20:21], 0, v[142:143]
	s_mov_b32 m0, s93
	s_nop 0
	global_load_lds_dwordx4 v[102:103], off
	s_waitcnt vmcnt(8)
	s_waitcnt lgkmcnt(0)
	s_barrier
	s_setprio 1
	s_waitcnt lgkmcnt(0)
	v_mfma_f32_16x16x32_bf16 v[60:63], v[132:135], v[204:207], v[60:63]
	v_mfma_f32_16x16x32_bf16 v[56:59], v[160:163], v[204:207], v[56:59]
	v_mfma_f32_16x16x32_bf16 v[52:55], v[132:135], v[228:231], v[52:55]
	v_mfma_f32_16x16x32_bf16 v[48:51], v[160:163], v[228:231], v[48:51]
	v_mfma_f32_16x16x32_bf16 v[44:47], v[132:135], v[236:239], v[44:47]
	v_mfma_f32_16x16x32_bf16 v[40:43], v[160:163], v[236:239], v[40:43]
	v_mfma_f32_16x16x32_bf16 v[36:39], v[132:135], v[244:247], v[36:39]
	v_mfma_f32_16x16x32_bf16 v[32:35], v[160:163], v[244:247], v[32:35]
	v_mfma_f32_16x16x32_bf16 v[60:63], v[136:139], v[224:227], v[60:63]
	v_mfma_f32_16x16x32_bf16 v[56:59], v[164:167], v[224:227], v[56:59]
	v_mfma_f32_16x16x32_bf16 v[52:55], v[136:139], v[232:235], v[52:55]
	v_mfma_f32_16x16x32_bf16 v[48:51], v[164:167], v[232:235], v[48:51]
	v_mfma_f32_16x16x32_bf16 v[44:47], v[136:139], v[240:243], v[44:47]
	v_mfma_f32_16x16x32_bf16 v[40:43], v[164:167], v[240:243], v[40:43]
	v_mfma_f32_16x16x32_bf16 v[36:39], v[136:139], v[248:251], v[36:39]
	v_mfma_f32_16x16x32_bf16 v[32:35], v[164:167], v[248:251], v[32:35]
	v_mfma_f32_16x16x32_bf16 v[28:31], v[168:171], v[204:207], v[28:31]
	v_mfma_f32_16x16x32_bf16 v[24:27], v[216:219], v[204:207], v[24:27]
	v_mfma_f32_16x16x32_bf16 v[20:23], v[168:171], v[228:231], v[20:23]
	v_mfma_f32_16x16x32_bf16 v[16:19], v[216:219], v[228:231], v[16:19]
	v_mfma_f32_16x16x32_bf16 v[12:15], v[168:171], v[236:239], v[12:15]
	v_mfma_f32_16x16x32_bf16 v[8:11], v[216:219], v[236:239], v[8:11]
	v_mfma_f32_16x16x32_bf16 v[4:7], v[168:171], v[244:247], v[4:7]
	v_mfma_f32_16x16x32_bf16 v[0:3], v[216:219], v[244:247], v[0:3]
	v_mfma_f32_16x16x32_bf16 v[28:31], v[172:175], v[224:227], v[28:31]
	v_mfma_f32_16x16x32_bf16 v[24:27], v[220:223], v[224:227], v[24:27]
	v_mfma_f32_16x16x32_bf16 v[20:23], v[172:175], v[232:235], v[20:23]
	v_mfma_f32_16x16x32_bf16 v[16:19], v[220:223], v[232:235], v[16:19]
	v_mfma_f32_16x16x32_bf16 v[12:15], v[172:175], v[240:243], v[12:15]
	v_mfma_f32_16x16x32_bf16 v[8:11], v[220:223], v[240:243], v[8:11]
	v_mfma_f32_16x16x32_bf16 v[4:7], v[172:175], v[248:251], v[4:7]
	v_mfma_f32_16x16x32_bf16 v[0:3], v[220:223], v[248:251], v[0:3]
	s_setprio 0
	s_barrier
; #define PG8_STAGE(bufoff, gbase, voff) do { _Pragma("unroll") for (int _i = 0; _i < 2; ++_i) \
;         __builtin_amdgcn_global_load_lds((const unsigned*)((const char*)(gbase) + (voff)[_i]), (LAS unsigned*)(lds + (bufoff) + ldsw + _i * 8192), 16, 0, 0); } while (0)
; #define PG8_LDA(dst, b, h) do { _Pragma("unroll") for (int m = 0; m < 4; ++m) _Pragma("unroll") for (int k = 0; k < 2; ++k) dst[m][k] = *(const LAS bf16x8*)(lds + PG8_SA(b, h) + aoff + m * 2048 + k * 1024); } while (0)
; #define PG8_LDB(dst, b, h) do { _Pragma("unroll") for (int n = 0; n < 2; ++n) _Pragma("unroll") for (int k = 0; k < 2; ++k) dst[n][k] = *(const LAS bf16x8*)(lds + PG8_SB(b, h) + boff + n * 2048 + k * 1024); } while (0)
; #define PG8_MMA(ai, bj, At, Bt) do { __builtin_amdgcn_s_setprio(1); _Pragma("unroll") for (int m = 0; m < 4; ++m) _Pragma("unroll") for (int n = 0; n < 2; ++n) _Pragma("unroll") for (int k = 0; k < 2; ++k) \
;         acc[ai][bj][m][n] = __builtin_amdgcn_mfma_f32_16x16x32_bf16(Bt[n][k], At[m][k], acc[ai][bj][m][n], 0, 0, 0); __builtin_amdgcn_s_setprio(0); } while (0)
; #define PG8_WAIT_V(n) asm volatile("s_waitcnt vmcnt(" #n ")" ::: "memory")
; #define PG8_WAIT_L(n) asm volatile("s_waitcnt lgkmcnt(" #n ")" ::: "memory")
; #define PG8_BAR __builtin_amdgcn_s_barrier()
; #define PG8_SCHED __builtin_amdgcn_sched_barrier(0)
; __device__ __forceinline__ void gemm_phase(LAS unsigned char* lds, const GemmP g, const EpiP e) {
;     ...
;             PG8_LDB(B0, 1, 0); PG8_LDB(B1, 1, 1); PG8_SCHED; PG8_LDA(At, 1, 0); PG8_STAGE(PG8_SA(0, 1), a2 + hstepA, voffA);
;             PG8_WAIT_V(8); PG8_WAIT_L(0); PG8_BAR; PG8_MMA(0, 0, At, B0); PG8_MMA(0, 1, At, B1); PG8_BAR; PG8_SCHED;
;             PG8_LDA(At, 1, 1); PG8_STAGE(PG8_SB(1, 0), b3, voffB); PG8_STAGE(PG8_SB(1, 1), b3 + hstepB, voffB); PG8_STAGE(PG8_SA(1, 0), a3, voffA);
;             PG8_WAIT_V(8); PG8_WAIT_L(0); PG8_BAR; PG8_MMA(1, 0, At, B0); PG8_MMA(1, 1, At, B1); PG8_BAR; PG8_SCHED;
;         }
	s_add_i32 s22, 0, 0x18000
	v_add_u32_e32 v96, s22, v179
	s_add_i32 s23, 0, 0x1c000
	ds_read_b128 v[132:135], v96
	ds_read_b128 v[136:139], v96 offset:1024
	ds_read_b128 v[160:163], v96 offset:2048
	ds_read_b128 v[164:167], v96 offset:3072
	v_add_u32_e32 v96, s23, v179
	ds_read_b128 v[168:171], v96
	ds_read_b128 v[172:175], v96 offset:1024
	ds_read_b128 v[204:207], v96 offset:2048
	ds_read_b128 v[216:219], v96 offset:3072
	s_add_u32 s20, s20, s90
	s_addc_u32 s21, s21, s7
	s_mov_b32 m0, s73
	v_lshl_add_u64 v[102:103], s[20:21], 0, v[140:141]
	ds_read_b128 v[220:223], v188 offset:32768
	ds_read_b128 v[224:227], v188 offset:33792
	ds_read_b128 v[228:231], v188 offset:34816
	ds_read_b128 v[232:235], v188 offset:35840
	ds_read_b128 v[236:239], v188 offset:36864
	ds_read_b128 v[240:243], v188 offset:37888
	ds_read_b128 v[244:247], v188 offset:38912
	ds_read_b128 v[248:251], v188 offset:39936
	global_load_lds_dwordx4 v[102:103], off
	v_lshl_add_u64 v[102:103], s[20:21], 0, v[142:143]
	s_mov_b32 m0, s4
	s_nop 0
	global_load_lds_dwordx4 v[102:103], off
	s_waitcnt vmcnt(8)
	s_waitcnt lgkmcnt(0)
	s_barrier
	s_setprio 1
	s_waitcnt lgkmcnt(0)
	v_mfma_f32_16x16x32_bf16 v[128:131], v[132:135], v[220:223], v[128:131]
	v_mfma_f32_16x16x32_bf16 v[124:127], v[160:163], v[220:223], v[124:127]
	v_mfma_f32_16x16x32_bf16 v[120:123], v[132:135], v[228:231], v[120:123]
	v_mfma_f32_16x16x32_bf16 v[116:119], v[160:163], v[228:231], v[116:119]
	v_mfma_f32_16x16x32_bf16 v[112:115], v[132:135], v[236:239], v[112:115]
	v_mfma_f32_16x16x32_bf16 v[108:111], v[160:163], v[236:239], v[108:111]
	v_mfma_f32_16x16x32_bf16 v[102:105], v[132:135], v[244:247], v[104:107]
	v_mfma_f32_16x16x32_bf16 v[98:101], v[160:163], v[244:247], v[98:101]
	v_mfma_f32_16x16x32_bf16 v[128:131], v[136:139], v[224:227], v[128:131]
	v_mfma_f32_16x16x32_bf16 v[124:127], v[164:167], v[224:227], v[124:127]
	v_mfma_f32_16x16x32_bf16 v[120:123], v[136:139], v[232:235], v[120:123]
	v_mfma_f32_16x16x32_bf16 v[116:119], v[164:167], v[232:235], v[116:119]
	v_mfma_f32_16x16x32_bf16 v[112:115], v[136:139], v[240:243], v[112:115]
	v_mfma_f32_16x16x32_bf16 v[108:111], v[164:167], v[240:243], v[108:111]
	v_mfma_f32_16x16x32_bf16 v[104:107], v[136:139], v[248:251], v[102:105]
	v_mfma_f32_16x16x32_bf16 v[100:103], v[164:167], v[248:251], v[98:101]
	v_mfma_f32_16x16x32_bf16 v[92:95], v[168:171], v[220:223], v[92:95]
	v_mfma_f32_16x16x32_bf16 v[88:91], v[204:207], v[220:223], v[88:91]
	v_mfma_f32_16x16x32_bf16 v[84:87], v[168:171], v[228:231], v[84:87]
	v_mfma_f32_16x16x32_bf16 v[80:83], v[204:207], v[228:231], v[80:83]
	v_mfma_f32_16x16x32_bf16 v[76:79], v[168:171], v[236:239], v[76:79]
	v_mfma_f32_16x16x32_bf16 v[72:75], v[204:207], v[236:239], v[72:75]
	v_mfma_f32_16x16x32_bf16 v[68:71], v[168:171], v[244:247], v[68:71]
	v_mfma_f32_16x16x32_bf16 v[64:67], v[204:207], v[244:247], v[64:67]
	v_mfma_f32_16x16x32_bf16 v[92:95], v[172:175], v[224:227], v[92:95]
	v_mfma_f32_16x16x32_bf16 v[88:91], v[216:219], v[224:227], v[88:91]
	v_mfma_f32_16x16x32_bf16 v[84:87], v[172:175], v[232:235], v[84:87]
	v_mfma_f32_16x16x32_bf16 v[80:83], v[216:219], v[232:235], v[80:83]
	v_mfma_f32_16x16x32_bf16 v[76:79], v[172:175], v[240:243], v[76:79]
	v_mfma_f32_16x16x32_bf16 v[72:75], v[216:219], v[240:243], v[72:75]
	v_mfma_f32_16x16x32_bf16 v[68:71], v[172:175], v[248:251], v[68:71]
	v_mfma_f32_16x16x32_bf16 v[64:67], v[216:219], v[248:251], v[64:67]
	s_setprio 0
	s_barrier
	s_add_i32 s20, s22, s91
	v_lshl_add_u64 v[98:99], v[176:177], 0, s[96:97]
	s_mov_b32 m0, s20
	ds_read_b128 v[220:223], v188 offset:49152
	ds_read_b128 v[224:227], v188 offset:50176
	ds_read_b128 v[228:231], v188 offset:51200
	ds_read_b128 v[232:235], v188 offset:52224
	ds_read_b128 v[236:239], v188 offset:53248
	ds_read_b128 v[240:243], v188 offset:54272
	ds_read_b128 v[244:247], v188 offset:55296
	ds_read_b128 v[248:251], v188 offset:56320
	global_load_lds_dwordx4 v[98:99], off
	v_lshl_add_u64 v[98:99], v[210:211], 0, s[96:97]
	s_add_i32 m0, s20, 0x2000
	s_add_i32 s20, s23, s91
	global_load_lds_dwordx4 v[98:99], off
	v_lshl_add_u64 v[98:99], v[212:213], 0, s[96:97]
	s_mov_b32 m0, s20
	s_nop 0
	global_load_lds_dwordx4 v[98:99], off
	v_lshl_add_u64 v[98:99], v[190:191], 0, s[96:97]
	s_add_i32 m0, s20, 0x2000
	s_nop 0
	global_load_lds_dwordx4 v[98:99], off
	v_lshl_add_u64 v[98:99], s[18:19], 0, v[140:141]
	s_mov_b32 m0, s5
	s_nop 0
	global_load_lds_dwordx4 v[98:99], off
	v_lshl_add_u64 v[98:99], s[18:19], 0, v[142:143]
	s_mov_b32 m0, s44
	s_nop 0
	global_load_lds_dwordx4 v[98:99], off
	s_waitcnt vmcnt(8)
	s_waitcnt lgkmcnt(0)
	s_barrier
	s_setprio 1
	s_waitcnt lgkmcnt(0)
	v_mfma_f32_16x16x32_bf16 v[60:63], v[132:135], v[220:223], v[60:63]
	v_mfma_f32_16x16x32_bf16 v[56:59], v[160:163], v[220:223], v[56:59]
	v_mfma_f32_16x16x32_bf16 v[52:55], v[132:135], v[228:231], v[52:55]
	v_mfma_f32_16x16x32_bf16 v[48:51], v[160:163], v[228:231], v[48:51]
	v_mfma_f32_16x16x32_bf16 v[44:47], v[132:135], v[236:239], v[44:47]
	v_mfma_f32_16x16x32_bf16 v[40:43], v[160:163], v[236:239], v[40:43]
	v_mfma_f32_16x16x32_bf16 v[36:39], v[132:135], v[244:247], v[36:39]
	v_mfma_f32_16x16x32_bf16 v[32:35], v[160:163], v[244:247], v[32:35]
	v_mfma_f32_16x16x32_bf16 v[60:63], v[136:139], v[224:227], v[60:63]
	v_mfma_f32_16x16x32_bf16 v[56:59], v[164:167], v[224:227], v[56:59]
	v_mfma_f32_16x16x32_bf16 v[52:55], v[136:139], v[232:235], v[52:55]
	v_mfma_f32_16x16x32_bf16 v[48:51], v[164:167], v[232:235], v[48:51]
	v_mfma_f32_16x16x32_bf16 v[44:47], v[136:139], v[240:243], v[44:47]
	v_mfma_f32_16x16x32_bf16 v[40:43], v[164:167], v[240:243], v[40:43]
	v_mfma_f32_16x16x32_bf16 v[36:39], v[136:139], v[248:251], v[36:39]
	v_mfma_f32_16x16x32_bf16 v[32:35], v[164:167], v[248:251], v[32:35]
	v_mfma_f32_16x16x32_bf16 v[28:31], v[168:171], v[220:223], v[28:31]
	v_mfma_f32_16x16x32_bf16 v[24:27], v[204:207], v[220:223], v[24:27]
	v_mfma_f32_16x16x32_bf16 v[20:23], v[168:171], v[228:231], v[20:23]
	v_mfma_f32_16x16x32_bf16 v[16:19], v[204:207], v[228:231], v[16:19]
	v_mfma_f32_16x16x32_bf16 v[12:15], v[168:171], v[236:239], v[12:15]
	v_mfma_f32_16x16x32_bf16 v[8:11], v[204:207], v[236:239], v[8:11]
	v_mfma_f32_16x16x32_bf16 v[4:7], v[168:171], v[244:247], v[4:7]
	v_mfma_f32_16x16x32_bf16 v[0:3], v[204:207], v[244:247], v[0:3]
	v_mfma_f32_16x16x32_bf16 v[28:31], v[172:175], v[224:227], v[28:31]
	v_mfma_f32_16x16x32_bf16 v[24:27], v[216:219], v[224:227], v[24:27]
	v_mfma_f32_16x16x32_bf16 v[20:23], v[172:175], v[232:235], v[20:23]
	v_mfma_f32_16x16x32_bf16 v[16:19], v[216:219], v[232:235], v[16:19]
	v_mfma_f32_16x16x32_bf16 v[12:15], v[172:175], v[240:243], v[12:15]
	v_mfma_f32_16x16x32_bf16 v[8:11], v[216:219], v[240:243], v[8:11]
	v_mfma_f32_16x16x32_bf16 v[4:7], v[172:175], v[248:251], v[4:7]
	v_mfma_f32_16x16x32_bf16 v[0:3], v[216:219], v[248:251], v[0:3]
	s_setprio 0
	s_barrier
	s_add_u32 s27, s27, 0x100
	s_addc_u32 s28, s28, 0
	s_cmp_ge_i32 s16, s69
	s_mov_b64 s[18:19], s[16:17]
	s_cbranch_scc0 .LBB0_394
